# sc1 write-through on the final phase's 32 f32 output stores (end-of-kernel L2 flush)
# baseline (speedup 1.0000x reference)
.LBB0_1730:
	s_ashr_i32 s13, s48, 31
	s_lshr_b32 s13, s13, 28
	v_lshl_add_u32 v154, s48, 8, v0
	v_lshl_or_b32 v152, s66, 8, v17
	v_ashrrev_i32_e32 v155, 31, v154
	s_add_i32 s13, s48, s13
	v_ashrrev_i32_e32 v153, 31, v152
	v_lshlrev_b64 v[126:127], 11, v[154:155]
	s_ashr_i32 s13, s13, 4
	v_lshl_add_u64 v[150:151], v[126:127], 0, v[152:153]
	s_mul_hi_i32 s33, s13, 0xc000
	s_mul_i32 s13, s13, 0xc000
	v_lshl_add_u64 v[160:161], v[150:151], 1, s[8:9]
	s_add_u32 s50, s25, s13
	global_load_dwordx4 v[156:159], v[160:161], off
	s_addc_u32 s51, s28, s33
	v_lshl_add_u64 v[130:131], v[152:153], 2, s[50:51]
	global_load_dwordx4 v[138:141], v[130:131], off
	global_load_dwordx4 v[134:137], v[130:131], off offset:16
	v_lshl_add_u64 v[162:163], v[150:151], 2, s[4:5]
	global_load_dwordx4 v[126:129], v[130:131], off offset:528
	s_nop 0
	global_load_dwordx4 v[130:133], v[130:131], off offset:512
	s_mov_b64 s[50:51], 0x40000
	s_andn2_b64 vcc, exec, s[42:43]
	s_mov_b64 s[42:43], -1
	s_waitcnt vmcnt(0)
	v_lshlrev_b32_e32 v164, 16, v156
	v_and_b32_e32 v165, 0xffff0000, v156
	v_lshlrev_b32_e32 v156, 16, v157
	v_and_b32_e32 v157, 0xffff0000, v157
	v_lshlrev_b32_e32 v166, 16, v158
	v_and_b32_e32 v167, 0xffff0000, v158
	v_lshlrev_b32_e32 v158, 16, v159
	v_and_b32_e32 v159, 0xffff0000, v159
	v_pk_fma_f32 v[148:149], v[148:149], v[140:141], v[156:157]
	v_pk_fma_f32 v[146:147], v[146:147], v[138:139], v[164:165]
	v_pk_fma_f32 v[144:145], v[144:145], v[136:137], v[158:159]
	v_pk_fma_f32 v[142:143], v[142:143], v[134:135], v[166:167]
	global_store_dwordx4 v[162:163], v[146:149], off sc1
	global_store_dwordx4 v[162:163], v[142:145], off offset:16 sc1
	global_load_dwordx4 v[142:145], v[160:161], off offset:256
	v_or_b32_e32 v146, 16, v154
	v_ashrrev_i32_e32 v147, 31, v146
	v_lshlrev_b64 v[146:147], 11, v[146:147]
	v_lshl_add_u64 v[146:147], v[146:147], 0, v[152:153]
	v_lshl_add_u64 v[148:149], v[146:147], 1, s[8:9]
	s_waitcnt vmcnt(0)
	v_lshlrev_b32_e32 v156, 16, v142
	v_and_b32_e32 v157, 0xffff0000, v142
	v_lshlrev_b32_e32 v142, 16, v143
	v_and_b32_e32 v143, 0xffff0000, v143
	v_lshlrev_b32_e32 v158, 16, v144
	v_and_b32_e32 v159, 0xffff0000, v144
	v_lshlrev_b32_e32 v144, 16, v145
	v_and_b32_e32 v145, 0xffff0000, v145
	v_pk_fma_f32 v[124:125], v[124:125], v[132:133], v[142:143]
	v_pk_fma_f32 v[122:123], v[122:123], v[130:131], v[156:157]
	v_pk_fma_f32 v[120:121], v[120:121], v[128:129], v[144:145]
	v_pk_fma_f32 v[118:119], v[118:119], v[126:127], v[158:159]
	global_store_dwordx4 v[162:163], v[122:125], off offset:512 sc1
	global_store_dwordx4 v[162:163], v[118:121], off offset:528 sc1
	global_load_dwordx4 v[118:121], v[148:149], off
	v_lshl_add_u64 v[122:123], v[146:147], 2, s[4:5]
	s_waitcnt vmcnt(0)
	v_lshlrev_b32_e32 v124, 16, v118
	v_and_b32_e32 v125, 0xffff0000, v118
	v_lshlrev_b32_e32 v118, 16, v119
	v_and_b32_e32 v119, 0xffff0000, v119
	v_lshlrev_b32_e32 v142, 16, v120
	v_and_b32_e32 v143, 0xffff0000, v120
	v_lshlrev_b32_e32 v120, 16, v121
	v_and_b32_e32 v121, 0xffff0000, v121
	v_pk_fma_f32 v[116:117], v[116:117], v[140:141], v[118:119]
	v_pk_fma_f32 v[114:115], v[114:115], v[138:139], v[124:125]
	v_pk_fma_f32 v[112:113], v[112:113], v[136:137], v[120:121]
	v_pk_fma_f32 v[110:111], v[110:111], v[134:135], v[142:143]
	global_store_dwordx4 v[122:123], v[114:117], off sc1
	global_store_dwordx4 v[122:123], v[110:113], off offset:16 sc1
	global_load_dwordx4 v[110:113], v[148:149], off offset:256
	v_or_b32_e32 v114, 32, v154
	v_ashrrev_i32_e32 v115, 31, v114
	v_lshlrev_b64 v[114:115], 11, v[114:115]
	v_lshl_add_u64 v[114:115], v[114:115], 0, v[152:153]
	v_lshl_add_u64 v[116:117], v[114:115], 1, s[8:9]
	s_waitcnt vmcnt(0)
	v_lshlrev_b32_e32 v118, 16, v110
	v_and_b32_e32 v119, 0xffff0000, v110
	v_lshlrev_b32_e32 v110, 16, v111
	v_and_b32_e32 v111, 0xffff0000, v111
	v_lshlrev_b32_e32 v120, 16, v112
	v_and_b32_e32 v121, 0xffff0000, v112
	v_lshlrev_b32_e32 v112, 16, v113
	v_and_b32_e32 v113, 0xffff0000, v113
	v_pk_fma_f32 v[108:109], v[108:109], v[132:133], v[110:111]
	v_pk_fma_f32 v[106:107], v[106:107], v[130:131], v[118:119]
	v_pk_fma_f32 v[104:105], v[104:105], v[128:129], v[112:113]
	v_pk_fma_f32 v[102:103], v[102:103], v[126:127], v[120:121]
	global_store_dwordx4 v[122:123], v[106:109], off offset:512 sc1
	global_store_dwordx4 v[122:123], v[102:105], off offset:528 sc1
	global_load_dwordx4 v[102:105], v[116:117], off
	v_lshl_add_u64 v[106:107], v[114:115], 2, s[4:5]
	s_waitcnt vmcnt(0)
	v_lshlrev_b32_e32 v108, 16, v102
	v_and_b32_e32 v109, 0xffff0000, v102
	v_lshlrev_b32_e32 v102, 16, v103
	v_and_b32_e32 v103, 0xffff0000, v103
	v_lshlrev_b32_e32 v110, 16, v104
	v_and_b32_e32 v111, 0xffff0000, v104
	v_lshlrev_b32_e32 v104, 16, v105
	v_and_b32_e32 v105, 0xffff0000, v105
	v_pk_fma_f32 v[100:101], v[100:101], v[140:141], v[102:103]
	v_pk_fma_f32 v[98:99], v[98:99], v[138:139], v[108:109]
	v_pk_fma_f32 v[96:97], v[96:97], v[136:137], v[104:105]
	v_pk_fma_f32 v[94:95], v[94:95], v[134:135], v[110:111]
	global_store_dwordx4 v[106:107], v[98:101], off sc1
	global_store_dwordx4 v[106:107], v[94:97], off offset:16 sc1
	global_load_dwordx4 v[94:97], v[116:117], off offset:256
	v_or_b32_e32 v98, 48, v154
	v_ashrrev_i32_e32 v99, 31, v98
	v_lshlrev_b64 v[98:99], 11, v[98:99]
	v_lshl_add_u64 v[98:99], v[98:99], 0, v[152:153]
	v_lshl_add_u64 v[100:101], v[98:99], 1, s[8:9]
	s_waitcnt vmcnt(0)
	v_lshlrev_b32_e32 v102, 16, v94
	v_and_b32_e32 v103, 0xffff0000, v94
	v_lshlrev_b32_e32 v94, 16, v95
	v_and_b32_e32 v95, 0xffff0000, v95
	v_lshlrev_b32_e32 v104, 16, v96
	v_and_b32_e32 v105, 0xffff0000, v96
	v_lshlrev_b32_e32 v96, 16, v97
	v_and_b32_e32 v97, 0xffff0000, v97
	v_pk_fma_f32 v[92:93], v[92:93], v[132:133], v[94:95]
	v_pk_fma_f32 v[90:91], v[90:91], v[130:131], v[102:103]
	v_pk_fma_f32 v[88:89], v[88:89], v[128:129], v[96:97]
	v_pk_fma_f32 v[86:87], v[86:87], v[126:127], v[104:105]
	global_store_dwordx4 v[106:107], v[90:93], off offset:512 sc1
	global_store_dwordx4 v[106:107], v[86:89], off offset:528 sc1
	global_load_dwordx4 v[86:89], v[100:101], off
	v_lshl_add_u64 v[90:91], v[98:99], 2, s[4:5]
	s_waitcnt vmcnt(0)
	v_lshlrev_b32_e32 v92, 16, v86
	v_and_b32_e32 v93, 0xffff0000, v86
	v_lshlrev_b32_e32 v86, 16, v87
	v_and_b32_e32 v87, 0xffff0000, v87
	v_lshlrev_b32_e32 v94, 16, v88
	v_and_b32_e32 v95, 0xffff0000, v88
	v_lshlrev_b32_e32 v88, 16, v89
	v_and_b32_e32 v89, 0xffff0000, v89
	v_pk_fma_f32 v[84:85], v[84:85], v[140:141], v[86:87]
	v_pk_fma_f32 v[82:83], v[82:83], v[138:139], v[92:93]
	v_pk_fma_f32 v[80:81], v[80:81], v[136:137], v[88:89]
	v_pk_fma_f32 v[78:79], v[78:79], v[134:135], v[94:95]
	global_store_dwordx4 v[90:91], v[82:85], off sc1
	global_store_dwordx4 v[90:91], v[78:81], off offset:16 sc1
	global_load_dwordx4 v[78:81], v[100:101], off offset:256
	v_lshl_add_u64 v[82:83], v[150:151], 0, s[50:51]
	v_lshl_add_u64 v[84:85], v[82:83], 1, s[8:9]
	s_mov_b64 s[50:51], 0x48000
	s_waitcnt vmcnt(0)
	v_lshlrev_b32_e32 v86, 16, v78
	v_and_b32_e32 v87, 0xffff0000, v78
	v_lshlrev_b32_e32 v78, 16, v79
	v_and_b32_e32 v79, 0xffff0000, v79
	v_lshlrev_b32_e32 v88, 16, v80
	v_and_b32_e32 v89, 0xffff0000, v80
	v_lshlrev_b32_e32 v80, 16, v81
	v_and_b32_e32 v81, 0xffff0000, v81
	v_pk_fma_f32 v[76:77], v[76:77], v[132:133], v[78:79]
	v_pk_fma_f32 v[74:75], v[74:75], v[130:131], v[86:87]
	v_pk_fma_f32 v[72:73], v[72:73], v[128:129], v[80:81]
	v_pk_fma_f32 v[70:71], v[70:71], v[126:127], v[88:89]
	global_store_dwordx4 v[90:91], v[74:77], off offset:512 sc1
	global_store_dwordx4 v[90:91], v[70:73], off offset:528 sc1
	global_load_dwordx4 v[70:73], v[84:85], off
	v_lshl_add_u64 v[74:75], v[82:83], 2, s[4:5]
	s_waitcnt vmcnt(0)
	v_lshlrev_b32_e32 v76, 16, v70
	v_and_b32_e32 v77, 0xffff0000, v70
	v_lshlrev_b32_e32 v70, 16, v71
	v_and_b32_e32 v71, 0xffff0000, v71
	v_lshlrev_b32_e32 v78, 16, v72
	v_and_b32_e32 v79, 0xffff0000, v72
	v_lshlrev_b32_e32 v72, 16, v73
	v_and_b32_e32 v73, 0xffff0000, v73
	v_pk_fma_f32 v[68:69], v[68:69], v[140:141], v[70:71]
	v_pk_fma_f32 v[66:67], v[66:67], v[138:139], v[76:77]
	v_pk_fma_f32 v[64:65], v[64:65], v[136:137], v[72:73]
	v_pk_fma_f32 v[62:63], v[62:63], v[134:135], v[78:79]
	global_store_dwordx4 v[74:75], v[66:69], off sc1
	global_store_dwordx4 v[74:75], v[62:65], off offset:16 sc1
	global_load_dwordx4 v[62:65], v[84:85], off offset:256
	v_lshl_add_u64 v[66:67], v[150:151], 0, s[50:51]
	v_lshl_add_u64 v[68:69], v[66:67], 1, s[8:9]
	s_mov_b64 s[50:51], 0x50000
	s_waitcnt vmcnt(0)
	v_lshlrev_b32_e32 v70, 16, v62
	v_and_b32_e32 v71, 0xffff0000, v62
	v_lshlrev_b32_e32 v62, 16, v63
	v_and_b32_e32 v63, 0xffff0000, v63
	v_lshlrev_b32_e32 v72, 16, v64
	v_and_b32_e32 v73, 0xffff0000, v64
	v_lshlrev_b32_e32 v64, 16, v65
	v_and_b32_e32 v65, 0xffff0000, v65
	v_pk_fma_f32 v[60:61], v[60:61], v[132:133], v[62:63]
	v_pk_fma_f32 v[58:59], v[58:59], v[130:131], v[70:71]
	v_pk_fma_f32 v[56:57], v[56:57], v[128:129], v[64:65]
	v_pk_fma_f32 v[54:55], v[54:55], v[126:127], v[72:73]
	global_store_dwordx4 v[74:75], v[58:61], off offset:512 sc1
	global_store_dwordx4 v[74:75], v[54:57], off offset:528 sc1
	global_load_dwordx4 v[54:57], v[68:69], off
	v_lshl_add_u64 v[58:59], v[66:67], 2, s[4:5]
	s_waitcnt vmcnt(0)
	v_lshlrev_b32_e32 v60, 16, v54
	v_and_b32_e32 v61, 0xffff0000, v54
	v_lshlrev_b32_e32 v54, 16, v55
	v_and_b32_e32 v55, 0xffff0000, v55
	v_lshlrev_b32_e32 v62, 16, v56
	v_and_b32_e32 v63, 0xffff0000, v56
	v_lshlrev_b32_e32 v56, 16, v57
	v_and_b32_e32 v57, 0xffff0000, v57
	v_pk_fma_f32 v[52:53], v[52:53], v[140:141], v[54:55]
	v_pk_fma_f32 v[50:51], v[50:51], v[138:139], v[60:61]
	v_pk_fma_f32 v[48:49], v[48:49], v[136:137], v[56:57]
	v_pk_fma_f32 v[46:47], v[46:47], v[134:135], v[62:63]
	global_store_dwordx4 v[58:59], v[50:53], off sc1
	global_store_dwordx4 v[58:59], v[46:49], off offset:16 sc1
	global_load_dwordx4 v[46:49], v[68:69], off offset:256
	v_lshl_add_u64 v[50:51], v[150:151], 0, s[50:51]
	v_lshl_add_u64 v[52:53], v[50:51], 1, s[8:9]
	s_mov_b64 s[50:51], 0x58000
	s_waitcnt vmcnt(0)
	v_lshlrev_b32_e32 v54, 16, v46
	v_and_b32_e32 v55, 0xffff0000, v46
	v_lshlrev_b32_e32 v46, 16, v47
	v_and_b32_e32 v47, 0xffff0000, v47
	v_lshlrev_b32_e32 v56, 16, v48
	v_and_b32_e32 v57, 0xffff0000, v48
	v_lshlrev_b32_e32 v48, 16, v49
	v_and_b32_e32 v49, 0xffff0000, v49
	v_pk_fma_f32 v[44:45], v[44:45], v[132:133], v[46:47]
	v_pk_fma_f32 v[42:43], v[42:43], v[130:131], v[54:55]
	v_pk_fma_f32 v[40:41], v[40:41], v[128:129], v[48:49]
	v_pk_fma_f32 v[38:39], v[38:39], v[126:127], v[56:57]
	global_store_dwordx4 v[58:59], v[42:45], off offset:512 sc1
	global_store_dwordx4 v[58:59], v[38:41], off offset:528 sc1
	global_load_dwordx4 v[38:41], v[52:53], off
	v_lshl_add_u64 v[42:43], v[50:51], 2, s[4:5]
	s_waitcnt vmcnt(0)
	v_lshlrev_b32_e32 v44, 16, v38
	v_and_b32_e32 v45, 0xffff0000, v38
	v_lshlrev_b32_e32 v38, 16, v39
	v_and_b32_e32 v39, 0xffff0000, v39
	v_lshlrev_b32_e32 v46, 16, v40
	v_and_b32_e32 v47, 0xffff0000, v40
	v_lshlrev_b32_e32 v40, 16, v41
	v_and_b32_e32 v41, 0xffff0000, v41
	v_pk_fma_f32 v[36:37], v[36:37], v[140:141], v[38:39]
	v_pk_fma_f32 v[34:35], v[34:35], v[138:139], v[44:45]
	v_pk_fma_f32 v[32:33], v[32:33], v[136:137], v[40:41]
	v_pk_fma_f32 v[30:31], v[30:31], v[134:135], v[46:47]
	global_store_dwordx4 v[42:43], v[34:37], off sc1
	global_store_dwordx4 v[42:43], v[30:33], off offset:16 sc1
	global_load_dwordx4 v[30:33], v[52:53], off offset:256
	v_lshl_add_u64 v[34:35], v[150:151], 0, s[50:51]
	v_lshl_add_u64 v[36:37], v[34:35], 1, s[8:9]
	s_waitcnt vmcnt(0)
	v_lshlrev_b32_e32 v38, 16, v30
	v_and_b32_e32 v39, 0xffff0000, v30
	v_lshlrev_b32_e32 v30, 16, v31
	v_and_b32_e32 v31, 0xffff0000, v31
	v_lshlrev_b32_e32 v40, 16, v32
	v_and_b32_e32 v41, 0xffff0000, v32
	v_lshlrev_b32_e32 v32, 16, v33
	v_and_b32_e32 v33, 0xffff0000, v33
	v_pk_fma_f32 v[28:29], v[28:29], v[132:133], v[30:31]
	v_pk_fma_f32 v[26:27], v[26:27], v[130:131], v[38:39]
	v_pk_fma_f32 v[24:25], v[24:25], v[128:129], v[32:33]
	v_pk_fma_f32 v[22:23], v[22:23], v[126:127], v[40:41]
	global_store_dwordx4 v[42:43], v[26:29], off offset:512 sc1
	global_store_dwordx4 v[42:43], v[22:25], off offset:528 sc1
	global_load_dwordx4 v[22:25], v[36:37], off
	v_lshl_add_u64 v[26:27], v[34:35], 2, s[4:5]
	s_waitcnt vmcnt(0)
	v_lshlrev_b32_e32 v28, 16, v22
	v_and_b32_e32 v29, 0xffff0000, v22
	v_lshlrev_b32_e32 v22, 16, v23
	v_and_b32_e32 v23, 0xffff0000, v23
	v_lshlrev_b32_e32 v30, 16, v24
	v_and_b32_e32 v31, 0xffff0000, v24
	v_lshlrev_b32_e32 v24, 16, v25
	v_and_b32_e32 v25, 0xffff0000, v25
	v_pk_fma_f32 v[20:21], v[20:21], v[140:141], v[22:23]
	v_pk_fma_f32 v[18:19], v[18:19], v[138:139], v[28:29]
	v_pk_fma_f32 v[12:13], v[12:13], v[136:137], v[24:25]
	v_pk_fma_f32 v[10:11], v[10:11], v[134:135], v[30:31]
	global_store_dwordx4 v[26:27], v[18:21], off sc1
	global_store_dwordx4 v[26:27], v[10:13], off offset:16 sc1
	global_load_dwordx4 v[10:13], v[36:37], off offset:256
	s_waitcnt vmcnt(0)
	v_lshlrev_b32_e32 v18, 16, v10
	v_and_b32_e32 v19, 0xffff0000, v10
	v_lshlrev_b32_e32 v10, 16, v11
	v_and_b32_e32 v11, 0xffff0000, v11
	v_lshlrev_b32_e32 v20, 16, v12
	v_and_b32_e32 v21, 0xffff0000, v12
	v_lshlrev_b32_e32 v12, 16, v13
	v_and_b32_e32 v13, 0xffff0000, v13
	v_pk_fma_f32 v[8:9], v[8:9], v[132:133], v[10:11]
	v_pk_fma_f32 v[6:7], v[6:7], v[130:131], v[18:19]
	v_pk_fma_f32 v[4:5], v[4:5], v[128:129], v[12:13]
	v_pk_fma_f32 v[2:3], v[2:3], v[126:127], v[20:21]
	global_store_dwordx4 v[26:27], v[6:9], off offset:512 sc1
	global_store_dwordx4 v[26:27], v[2:5], off offset:528 sc1
	s_cbranch_vccnz .LBB0_1708
	s_andn2_b64 vcc, exec, s[6:7]
	s_cbranch_vccnz .LBB0_1707
	s_barrier
	s_branch .LBB0_1707
